# strategy 4: static s_setprio 1 for waves 0-3 at entry, all per-segment priority flips deleted (on v_rm_m1)
# speedup vs baseline: 1.0112x; 1.0005x over previous
_Z6mk_fwd4Args:
	v_readfirstlane_b32 s99, v0
	s_nop 3
	s_and_b32 s99, s99, 0x3ff
	s_lshr_b32 s99, s99, 6
	s_cmp_ge_u32 s99, 4
	s_cbranch_scc1 .Lprio_done
	s_setprio 1
